# finmerge hardened: all GEMM row-sum loads agent-scope (sc1), cache invalidate after the rare sample-panel waits
# baseline (speedup 1.0000x reference)
.Lfm0_ok:
	buffer_inv sc1
	s_waitcnt vmcnt(0)
	s_mov_b32 s12, 0
	v_writelane_b32 v244, s12, 2
.Lfm0_done:
	v_writelane_b32 v240, s50, 59
	s_ashr_i32 s9, s7, 8
	v_and_b32_e32 v166, 15, v12
	v_writelane_b32 v240, s51, 60
	s_lshl_b32 s50, s9, 6
	s_cmp_eq_u64 s[16:17], 0
	s_cselect_b64 s[14:15], -1, 0
	s_cmp_eq_u32 s41, 1
	s_cselect_b64 s[12:13], -1, 0
	s_or_b64 s[38:39], s[14:15], s[12:13]
	s_waitcnt vmcnt(0)
	v_mov_b32_e32 v173, 0
	s_and_b64 vcc, exec, s[38:39]
	v_mov_b32_e32 v174, 0
	v_mov_b32_e32 v172, 0
	v_mov_b32_e32 v171, 0
	v_mov_b32_e32 v170, 0
	v_mov_b32_e32 v169, 0
	v_mov_b32_e32 v168, 0
	v_mov_b32_e32 v167, 0
	s_cbranch_vccnz .LBB0_125
	v_readlane_b32 s12, v244, 2
	s_cmp_lg_u32 s12, 0
	s_cbranch_scc1 .LBB0_125
	s_lshl_b32 s12, s6, 8
	s_add_i32 s12, s12, s50
	v_or_b32_e32 v0, s12, v166
	v_ashrrev_i32_e32 v1, 31, v0
	v_lshl_add_u64 v[0:1], v[0:1], 2, s[16:17]
	global_load_dword v167, v[0:1], off sc1
	global_load_dword v168, v[0:1], off offset:64 sc1
	global_load_dword v169, v[0:1], off offset:128 sc1
	global_load_dword v170, v[0:1], off offset:192 sc1
	global_load_dword v171, v[0:1], off offset:512 sc1
	global_load_dword v172, v[0:1], off offset:576 sc1
	global_load_dword v174, v[0:1], off offset:640 sc1
	global_load_dword v173, v[0:1], off offset:704 sc1

.Lfm2_ok:
	buffer_inv sc1
	s_waitcnt vmcnt(0)

.LBB0_158:
	s_andn2_b64 vcc, exec, s[78:79]
	s_cbranch_vccnz .LBB0_160
	v_lshl_add_u32 v0, s23, 8, v175
	v_ashrrev_i32_e32 v1, 31, v0
	v_lshl_add_u64 v[0:1], v[0:1], 2, s[16:17]
	global_load_dword v167, v[0:1], off sc1
	global_load_dword v168, v[0:1], off offset:64 sc1
	global_load_dword v169, v[0:1], off offset:128 sc1
	global_load_dword v170, v[0:1], off offset:192 sc1
	global_load_dword v171, v[0:1], off offset:512 sc1
	global_load_dword v172, v[0:1], off offset:576 sc1
	global_load_dword v174, v[0:1], off offset:640 sc1
	global_load_dword v173, v[0:1], off offset:704 sc1
